# combo2: combo1 plus the prompt-attention item's first V-block loads hoisted to the item start
# baseline (speedup 1.0000x reference)
; template <bool VT>
; __device__ __forceinline__ void attn_item(const Params& P, const bf16_t* qp, const bf16_t* kb0, const bf16_t* vb0, int qb, int nq, int r, int head, int lane, const bf16x8 I0, const bf16x8 I1) {
;     ...
;     UNROLL for (int c = 0; c < 4; ++c) qf[c] = ld8(qp + 16 * c);
;     bf16x8 k1[4], v1[4];
;     { const bf16_t* kp = kb0 + (size_t)(qb * 32 + tl) * 64; const bf16_t* vp = VT ? vb0 + (size_t)qb * 2048 : vb0 + (size_t)(qb * 32 + tl) * 64;
;       UNROLL for (int c = 0; c < 4; ++c) { kf[c] = ld8(kp + 16 * c); vf[c] = ld8(vp + (VT ? 512 : 16) * c); } }
;     { const int b1 = qb > 0 ? qb - 1 : 0;
;       const bf16_t* kp = kb0 + (size_t)(b1 * 32 + tl) * 64; const bf16_t* vp = VT ? vb0 + (size_t)b1 * 2048 : vb0 + (size_t)(b1 * 32 + tl) * 64;
;       UNROLL for (int c = 0; c < 4; ++c) { k1[c] = ld8(kp + 16 * c); v1[c] = ld8(vp + (VT ? 512 : 16) * c); } }
;     f32x16 o0 = zero16(), o1 = zero16();
;     float R = 1.f;
;     const bool qvalid = tl < nq;
;     for (int j = 0; j <= qb; ++j) {
;         bf16x8 k2[4], v2[4];
;         { const int b2 = (qb - j - 2) > 0 ? (qb - j - 2) : 0;
;           const bf16_t* kp = kb0 + (size_t)(b2 * 32 + tl) * 64; const bf16_t* vp = VT ? vb0 + (size_t)b2 * 2048 : vb0 + (size_t)(b2 * 32 + tl) * 64;
;           UNROLL for (int c = 0; c < 4; ++c) { k2[c] = ld8(kp + 16 * c); v2[c] = ld8(vp + (VT ? 512 : 16) * c); } }
;         f32x16 z = zero16();
;         UNROLL for (int c = 0; c < 4; ++c) z = MFMA32(kf[c], qf[c], z);
;         f32x16 vt0, vt1;
;         if (!VT) { vt0 = MFMA32(vf[0], I0, zero16()); vt0 = MFMA32(vf[1], I1, vt0); vt1 = MFMA32(vf[2], I0, zero16()); vt1 = MFMA32(vf[3], I1, vt1); }
;         float kp[16];
;         const bool diag = (j == 0);
;         UNROLL for (int i = 0; i < 16; ++i) {
;             const float k1 = __builtin_amdgcn_rcpf(1.f + __builtin_amdgcn_exp2f(z[i]));
;             const int si = 8 * (i >> 2) + 4 * hh + (i & 3);
;             kp[i] = (diag && !(si < tl && qvalid)) ? 1.f : k1;
;         }
;         float lo[4], hi[4], T[4];
;         UNROLL for (int g = 0; g < 4; ++g) {
;             const float G = (kp[4 * g] * kp[4 * g + 1]) * (kp[4 * g + 2] * kp[4 * g + 3]);
;             const auto sw = __builtin_amdgcn_permlane32_swap(__float_as_uint(G), __float_as_uint(G), false, false);
;             lo[g] = __uint_as_float(sw[0]); hi[g] = __uint_as_float(sw[1]);
.LBB0_854:
	v_lshrrev_b32_e32 v64, 8, v115
	v_mov_b32_e32 v65, v163
	v_lshlrev_b64 v[28:29], 20, v[64:65]
	v_lshlrev_b32_sdwa v65, v201, v115 dst_sel:DWORD dst_unused:UNUSED_PAD src0_sel:DWORD src1_sel:BYTE_0
	v_lshl_or_b32 v0, v160, 1, v28
	v_mov_b32_e32 v1, v29
	v_or_b32_e32 v4, v65, v159
	v_lshlrev_b32_sdwa v38, v202, v115 dst_sel:DWORD dst_unused:UNUSED_PAD src0_sel:DWORD src1_sel:BYTE_0
	v_lshl_add_u64 v[2:3], s[64:65], 0, v[0:1]
	v_lshlrev_b32_e32 v162, 7, v4
	v_lshl_add_u64 v[66:67], s[84:85], 0, v[0:1]
	v_or_b32_e32 v0, v38, v187
	v_lshl_add_u64 v[30:31], v[2:3], 0, v[162:163]
	v_lshlrev_b32_e32 v162, 1, v0
	v_lshl_add_u64 v[24:25], v[66:67], 0, v[162:163]
	global_load_dwordx4 v[0:3], v[24:25], off
	global_load_dwordx4 v[48:51], v[30:31], off
	global_load_dwordx4 v[16:19], v[24:25], off offset:32
	global_load_dwordx4 v[52:55], v[30:31], off offset:32
	global_load_dwordx4 v[20:23], v[24:25], off offset:64
	global_load_dwordx4 v[56:59], v[30:31], off offset:64
	s_nop 0
	global_load_dwordx4 v[24:27], v[24:25], off offset:96
	v_lshl_add_u64 v[68:69], v[182:183], 0, v[28:29]
	global_load_dwordx4 v[60:63], v[30:31], off offset:96
	v_lshlrev_b32_sdwa v162, v203, v115 dst_sel:DWORD dst_unused:UNUSED_PAD src0_sel:DWORD src1_sel:BYTE_0
	v_lshl_add_u64 v[36:37], v[68:69], 0, v[162:163]
	v_cmp_ne_u32_sdwa s[60:61], v115, v163 src0_sel:BYTE_0 src1_sel:DWORD
	global_load_dwordx4 v[88:91], v[36:37], off
	global_load_dwordx4 v[92:95], v[36:37], off offset:1024
	global_load_dwordx4 v[96:99], v[36:37], off offset:2048
	global_load_dwordx4 v[100:103], v[36:37], off offset:3072
	s_waitcnt vmcnt(10)
	v_mfma_f32_32x32x16_bf16 v[0:15], v[0:3], v[48:51], 0
	s_waitcnt vmcnt(8)
	v_mfma_f32_32x32x16_bf16 v[0:15], v[16:19], v[52:55], v[0:15]
	s_waitcnt vmcnt(6)
	v_mfma_f32_32x32x16_bf16 v[0:15], v[20:23], v[56:59], v[0:15]
	s_waitcnt vmcnt(4)
	v_mfma_f32_32x32x16_bf16 v[0:15], v[24:27], v[60:63], v[0:15]
	s_nop 11
	v_exp_f32_e32 v4, v4
	v_exp_f32_e32 v5, v5
	v_exp_f32_e32 v6, v6
	v_exp_f32_e32 v7, v7
	v_exp_f32_e32 v12, v12
	v_exp_f32_e32 v13, v13
	v_exp_f32_e32 v14, v14
	v_exp_f32_e32 v15, v15
	v_exp_f32_e32 v0, v0
	v_exp_f32_e32 v1, v1
	v_exp_f32_e32 v2, v2
	v_exp_f32_e32 v3, v3
	v_exp_f32_e32 v8, v8
	v_exp_f32_e32 v9, v9
	v_exp_f32_e32 v10, v10
	v_exp_f32_e32 v11, v11
	v_add_f32_e32 v4, 1.0, v4
	v_add_f32_e32 v5, 1.0, v5
	v_add_f32_e32 v6, 1.0, v6
	v_add_f32_e32 v7, 1.0, v7
	v_add_f32_e32 v12, 1.0, v12
	v_add_f32_e32 v13, 1.0, v13
	v_add_f32_e32 v14, 1.0, v14
	v_add_f32_e32 v15, 1.0, v15
	v_add_f32_e32 v0, 1.0, v0
	v_add_f32_e32 v1, 1.0, v1
	v_add_f32_e32 v2, 1.0, v2
	v_add_f32_e32 v3, 1.0, v3
	v_add_f32_e32 v8, 1.0, v8
	v_add_f32_e32 v9, 1.0, v9
	v_add_f32_e32 v10, 1.0, v10
	v_add_f32_e32 v11, 1.0, v11
	v_rcp_f32_e32 v4, v4
	v_rcp_f32_e32 v5, v5
	v_rcp_f32_e32 v6, v6
	v_rcp_f32_e32 v7, v7
	v_rcp_f32_e32 v12, v12
	v_rcp_f32_e32 v13, v13
	v_rcp_f32_e32 v14, v14
	v_rcp_f32_e32 v15, v15
	v_rcp_f32_e32 v0, v0
	v_rcp_f32_e32 v1, v1
	v_rcp_f32_e32 v2, v2
	v_rcp_f32_e32 v3, v3
	v_rcp_f32_e32 v8, v8
	v_rcp_f32_e32 v9, v9
	v_rcp_f32_e32 v10, v10
	v_rcp_f32_e32 v11, v11
	v_cndmask_b32_e64 v30, 1.0, v4, s[14:15]
	v_cndmask_b32_e64 v31, 1.0, v5, s[16:17]
	v_cndmask_b32_e64 v39, 1.0, v6, s[18:19]
	v_cndmask_b32_e64 v40, 1.0, v7, s[20:21]
	v_cndmask_b32_e64 v5, 1.0, v14, s[30:31]
	v_cndmask_b32_e64 v4, 1.0, v12, s[34:35]
	v_cndmask_b32_e64 v7, 1.0, v15, s[36:37]
	v_cndmask_b32_e64 v6, 1.0, v13, s[38:39]
	v_cndmask_b32_e64 v28, 1.0, v0, s[6:7]
	v_cndmask_b32_e64 v26, 1.0, v1, s[8:9]
	v_cndmask_b32_e64 v27, 1.0, v2, s[10:11]
	v_cndmask_b32_e64 v29, 1.0, v3, s[12:13]
	v_cndmask_b32_e64 v1, 1.0, v10, s[22:23]
	v_cndmask_b32_e64 v0, 1.0, v8, s[24:25]
	v_cndmask_b32_e64 v3, 1.0, v11, s[26:27]
	v_cndmask_b32_e64 v2, 1.0, v9, s[28:29]
	v_pk_mul_f32 v[10:11], v[4:5], v[6:7]
	v_pk_mul_f32 v[8:9], v[0:1], v[2:3]
	v_pk_mul_f32 v[10:11], v[10:11], v[10:11] op_sel:[0,1] op_sel_hi:[1,0]
	v_pk_mul_f32 v[8:9], v[8:9], v[8:9] op_sel:[0,1] op_sel_hi:[1,0]
	v_mov_b32_e32 v25, v10
	v_mul_f32_e32 v14, v30, v31
	v_mul_f32_e32 v15, v39, v40
	v_mov_b32_e32 v24, v8
	v_permlane32_swap_b32_e32 v10, v25
	v_mul_f32_e32 v14, v14, v15
	v_permlane32_swap_b32_e32 v8, v24
	v_mov_b32_e32 v9, v10
	v_mul_f32_e32 v12, v28, v26
	v_mul_f32_e32 v13, v27, v29
	v_mov_b32_e32 v22, v14
	v_pk_mul_f32 v[8:9], v[8:9], v[24:25]
	v_mul_f32_e32 v12, v12, v13
	v_permlane32_swap_b32_e32 v14, v22
	v_mov_b32_e32 v15, v8
	v_mov_b32_e32 v23, v9
	v_mov_b32_e32 v20, v12
	v_cndmask_b32_e64 v42, 1.0, v22, s[4:5]
	v_pk_mul_f32 v[10:11], v[14:15], v[22:23]
	v_permlane32_swap_b32_e32 v12, v20
	v_mov_b32_e32 v13, v10
	v_mov_b32_e32 v21, v11
	v_mul_f32_e32 v11, v42, v11
	v_cndmask_b32_e64 v41, 1.0, v20, s[4:5]
	v_pk_mul_f32 v[44:45], v[12:13], v[20:21]
	v_mul_f32_e32 v10, v40, v11
	v_mul_f32_e32 v13, v41, v45
	v_mul_f32_e32 v14, v39, v10
	v_cndmask_b32_e64 v8, 1.0, v24, s[4:5]
	v_cndmask_b32_e64 v47, 1.0, v25, s[4:5]
	v_mov_b32_e32 v15, v10
	v_mul_f32_e32 v12, v29, v13
	v_mul_f32_e32 v20, v31, v14
	v_mul_f32_e32 v9, v8, v9
	v_mul_f32_e32 v46, v7, v47
	v_pk_add_f32 v[10:11], v[10:11], v[14:15] neg_lo:[0,1] neg_hi:[0,1]
	v_mov_b32_e32 v21, v14
	v_mul_f32_e32 v14, v27, v12
	v_mov_b32_e32 v15, v12
	v_mul_f32_e32 v22, v30, v20
	v_mov_b32_e32 v23, v20
	v_mul_f32_e32 v8, v3, v9
	v_mul_f32_e32 v70, v5, v46
	v_pk_add_f32 v[12:13], v[12:13], v[14:15] neg_lo:[0,1] neg_hi:[0,1]
	v_mul_f32_e32 v26, v26, v14
	v_mov_b32_e32 v27, v14
	v_pk_add_f32 v[14:15], v[20:21], v[22:23] neg_lo:[0,1] neg_hi:[0,1]
	v_mul_f32_e32 v22, v1, v8
	v_mul_f32_e32 v6, v6, v70
	v_mul_f32_e32 v20, v28, v26
	v_mov_b32_e32 v21, v26
	v_mul_f32_e32 v2, v2, v22
	v_mul_f32_e32 v4, v4, v6
	v_mov_b32_e32 v7, v70
	v_mov_b32_e32 v5, v6
	v_pk_add_f32 v[20:21], v[26:27], v[20:21] neg_lo:[0,1] neg_hi:[0,1]
	v_mul_f32_e32 v0, v0, v2
	v_mov_b32_e32 v3, v22
	v_mov_b32_e32 v1, v2
	v_mov_b32_e32 v71, v46
	v_pk_add_f32 v[4:5], v[6:7], v[4:5] neg_lo:[0,1] neg_hi:[0,1]
	v_mov_b32_e32 v23, v8
	v_pk_add_f32 v[40:41], v[2:3], v[0:1] neg_lo:[0,1] neg_hi:[0,1]
	v_cvt_pk_bf16_f32 v0, v20, v21
	v_cvt_pk_bf16_f32 v1, v12, v13
	v_cvt_pk_bf16_f32 v2, v14, v15
	v_cvt_pk_bf16_f32 v3, v10, v11
	v_cvt_pk_bf16_f32 v42, v4, v5
	v_pk_add_f32 v[4:5], v[46:47], v[70:71] neg_lo:[0,1] neg_hi:[0,1]
	v_pk_add_f32 v[8:9], v[8:9], v[22:23] neg_lo:[0,1] neg_hi:[0,1]
	s_waitcnt vmcnt(3)
	v_mfma_f32_32x32x16_bf16 v[16:31], v[88:91], v[0:3], 0
	v_cvt_pk_bf16_f32 v43, v4, v5
	v_cvt_pk_bf16_f32 v40, v40, v41
	v_cvt_pk_bf16_f32 v41, v8, v9
	v_mul_f32_e32 v75, v44, v45
	v_cmp_nlt_f32_e32 vcc, 0, v75
	s_cmp_lg_u64 vcc, exec
	s_waitcnt vmcnt(2)
	v_mfma_f32_32x32x16_bf16 v[16:31], v[92:95], v[40:43], v[16:31]
	s_cselect_b64 s[2:3], -1, 0
	s_and_b64 s[2:3], s[60:61], s[2:3]
	s_waitcnt vmcnt(1)
	v_mfma_f32_32x32x16_bf16 v[0:15], v[96:99], v[0:3], 0
	s_waitcnt vmcnt(0)
	v_mfma_f32_32x32x16_bf16 v[0:15], v[100:103], v[40:43], v[0:15]
	s_and_saveexec_b64 s[60:61], s[2:3]
	s_cbranch_execz .LBB0_858
; #define UNROLL _Pragma("unroll")
; __device__ __forceinline__ f32x16 zero16() { f32x16 z; UNROLL for (int i = 0; i < 16; ++i) z[i] = 0.f; return z; }
; template <bool VT>
; __device__ __forceinline__ void attn_item(const Params& P, const bf16_t* qp, const bf16_t* kb0, const bf16_t* vb0, int qb, int nq, int r, int head, int lane, const bf16x8 I0, const bf16x8 I1) {
;     ...
;     { const int b1 = qb > 0 ? qb - 1 : 0;
;       const bf16_t* kp = kb0 + (size_t)(b1 * 32 + tl) * 64; const bf16_t* vp = VT ? vb0 + (size_t)b1 * 2048 : vb0 + (size_t)(b1 * 32 + tl) * 64;
;       UNROLL for (int c = 0; c < 4; ++c) { k1[c] = ld8(kp + 16 * c); v1[c] = ld8(vp + (VT ? 512 : 16) * c); } }
;     f32x16 o0 = zero16(), o1 = zero16();
;     float R = 1.f;
;     const bool qvalid = tl < nq;
;     for (int j = 0; j <= qb; ++j) {
;         bf16x8 k2[4], v2[4];
;         { const int b2 = (qb - j - 2) > 0 ? (qb - j - 2) : 0;
;           const bf16_t* kp = kb0 + (size_t)(b2 * 32 + tl) * 64; const bf16_t* vp = VT ? vb0 + (size_t)b2 * 2048 : vb0 + (size_t)(b2 * 32 + tl) * 64;
;           UNROLL for (int c = 0; c < 4; ++c) { k2[c] = ld8(kp + 16 * c); v2[c] = ld8(vp + (VT ? 512 : 16) * c); } }
	v_add_u32_e32 v162, 0xfffff800, v38
	v_lshl_add_u64 v[34:35], v[162:163], 1, v[68:69]
	v_or_b32_e32 v162, v162, v187
	v_add_u32_sdwa v74, v114, v204 dst_sel:DWORD dst_unused:UNUSED_PAD src0_sel:BYTE_0 src1_sel:DWORD
	v_sub_u32_sdwa v76, v115, v205 clamp dst_sel:DWORD dst_unused:UNUSED_PAD src0_sel:BYTE_0 src1_sel:DWORD
	s_mov_b32 s78, 1
	v_lshl_add_u64 v[32:33], v[162:163], 1, v[66:67]
	s_mov_b64 s[70:71], 0
